# attention loop rotated: barrier after M18, last 6 QK MFMAs run post-barrier interleaved with next tile V reads and global loads; PV k-step order permuted, in-place exps
# speedup vs baseline: 1.0265x; 1.0041x over previous
.LBB0_507:
	s_waitcnt lgkmcnt(5)
	v_mfma_f32_32x32x16_bf16 v[32:47], v[222:225], v[152:155], v[32:47]
	ds_read_b128 v[246:249], v192 offset:27744
	v_exp_f32_e32 v80, v80
	v_exp_f32_e32 v81, v81
	s_and_b32 s16, s15, 64
	s_mulk_i32 s16, 0x90
	v_add_f32_e32 v193, v80, v193
	v_add_f32_e32 v142, v81, v142
	v_add_u32_e32 v170, s16, v208
	s_waitcnt lgkmcnt(5)
	v_mfma_f32_32x32x16_bf16 v[64:79], v[226:229], v[152:155], v[64:79]
	ds_read_b128 v[250:253], v192 offset:32352
	v_exp_f32_e32 v82, v82
	v_exp_f32_e32 v83, v83
	s_add_i32 s93, s93, 1
	s_and_b32 s16, s93, 1
	v_add_f32_e32 v193, v82, v193
	v_add_f32_e32 v142, v83, v142
	s_mul_i32 s17, s16, 0x4800
	s_waitcnt lgkmcnt(5)
	v_mfma_f32_32x32x16_bf16 v[48:63], v[230:233], v[152:155], v[48:63]
	ds_read_b128 v[222:225], v192 offset:18432
	v_exp_f32_e32 v84, v84
	v_exp_f32_e32 v85, v85
	s_mulk_i32 s16, 0x2400
	s_add_i32 s15, s15, 64
	s_add_u32 s6, s6, 0x80
	s_addc_u32 s7, s7, 0
	s_cmp_eq_u32 s14, s93
	v_add_f32_e32 v193, v84, v193
	v_add_f32_e32 v142, v85, v142
	s_waitcnt lgkmcnt(5)
	v_mfma_f32_32x32x16_bf16 v[16:31], v[234:237], v[152:155], v[16:31]
	ds_read_b128 v[226:229], v192 offset:23040
	v_exp_f32_e32 v86, v86
	v_exp_f32_e32 v87, v87
	v_add_f32_e32 v193, v86, v193
	v_add_f32_e32 v142, v87, v142
	v_cvt_pk_bf16_f32 v152, v80, v81
	v_cvt_pk_bf16_f32 v153, v82, v83
	v_cvt_pk_bf16_f32 v154, v84, v85
	v_cvt_pk_bf16_f32 v155, v86, v87
	s_waitcnt lgkmcnt(5)
	v_mfma_f32_32x32x16_bf16 v[32:47], v[238:241], v[156:159], v[32:47]
	ds_read_b128 v[230:233], v192 offset:27648
	v_exp_f32_e32 v88, v88
	v_exp_f32_e32 v89, v89
	v_add_f32_e32 v193, v88, v193
	v_add_f32_e32 v142, v89, v142
	s_waitcnt lgkmcnt(5)
	v_mfma_f32_32x32x16_bf16 v[64:79], v[242:245], v[156:159], v[64:79]
	ds_read_b128 v[234:237], v192 offset:32256
	v_exp_f32_e32 v90, v90
	v_exp_f32_e32 v91, v91
	v_add_f32_e32 v193, v90, v193
	v_add_f32_e32 v142, v91, v142
	s_waitcnt lgkmcnt(5)
	v_mfma_f32_32x32x16_bf16 v[48:63], v[246:249], v[156:159], v[48:63]
	ds_read_b128 v[238:241], v192 offset:18464
	v_exp_f32_e32 v92, v92
	v_exp_f32_e32 v93, v93
	v_add_f32_e32 v193, v92, v193
	v_add_f32_e32 v142, v93, v142
	s_waitcnt lgkmcnt(5)
	v_mfma_f32_32x32x16_bf16 v[16:31], v[250:253], v[156:159], v[16:31]
	ds_read_b128 v[242:245], v192 offset:23072
	v_exp_f32_e32 v94, v94
	v_exp_f32_e32 v95, v95
	v_add_f32_e32 v193, v94, v193
	v_add_f32_e32 v142, v95, v142
	v_cvt_pk_bf16_f32 v156, v88, v89
	v_cvt_pk_bf16_f32 v157, v90, v91
	v_cvt_pk_bf16_f32 v158, v92, v93
	v_cvt_pk_bf16_f32 v159, v94, v95
	s_waitcnt lgkmcnt(5)
	v_mfma_f32_32x32x16_bf16 v[32:47], v[222:225], v[160:163], v[32:47]
	ds_read_b128 v[246:249], v192 offset:27680
	v_exp_f32_e32 v96, v96
	v_exp_f32_e32 v97, v97
	v_add_f32_e32 v193, v96, v193
	v_add_f32_e32 v142, v97, v142
	s_waitcnt lgkmcnt(5)
	v_mfma_f32_32x32x16_bf16 v[64:79], v[226:229], v[160:163], v[64:79]
	ds_read_b128 v[250:253], v192 offset:32288
	v_exp_f32_e32 v98, v98
	v_exp_f32_e32 v99, v99
	v_add_f32_e32 v193, v98, v193
	v_add_f32_e32 v142, v99, v142
	s_waitcnt lgkmcnt(5)
	v_mfma_f32_32x32x16_bf16 v[48:63], v[230:233], v[160:163], v[48:63]
	ds_read_b128 v[222:225], v170
	v_exp_f32_e32 v100, v100
	v_exp_f32_e32 v101, v101
	v_add_f32_e32 v193, v100, v193
	v_add_f32_e32 v142, v101, v142
	s_waitcnt lgkmcnt(5)
	v_mfma_f32_32x32x16_bf16 v[16:31], v[234:237], v[160:163], v[16:31]
	ds_read_b128 v[226:229], v170 offset:4608
	v_exp_f32_e32 v102, v102
	v_exp_f32_e32 v103, v103
	v_add_f32_e32 v193, v102, v193
	v_add_f32_e32 v142, v103, v142
	v_cvt_pk_bf16_f32 v160, v96, v97
	v_cvt_pk_bf16_f32 v161, v98, v99
	v_cvt_pk_bf16_f32 v162, v100, v101
	v_cvt_pk_bf16_f32 v163, v102, v103
	s_waitcnt lgkmcnt(5)
	v_mfma_f32_32x32x16_bf16 v[32:47], v[238:241], v[148:151], v[32:47]
	ds_read_b128 v[230:233], v170 offset:4640
	v_exp_f32_e32 v104, v104
	v_exp_f32_e32 v105, v105
	v_add_f32_e32 v193, v104, v193
	v_add_f32_e32 v142, v105, v142
	s_waitcnt lgkmcnt(5)
	v_mfma_f32_32x32x16_bf16 v[64:79], v[242:245], v[148:151], v[64:79]
	ds_read_b128 v[234:237], v170 offset:4672
	v_exp_f32_e32 v106, v106
	v_exp_f32_e32 v107, v107
	v_add_f32_e32 v193, v106, v193
	v_add_f32_e32 v142, v107, v142
	s_waitcnt lgkmcnt(5)
	v_mfma_f32_32x32x16_bf16 v[48:63], v[246:249], v[148:151], v[48:63]
	ds_read_b128 v[238:241], v170 offset:4704
	v_exp_f32_e32 v108, v108
	v_exp_f32_e32 v109, v109
	v_add_f32_e32 v193, v108, v193
	v_add_f32_e32 v142, v109, v142
	s_waitcnt lgkmcnt(5)
	v_mfma_f32_32x32x16_bf16 v[16:31], v[250:253], v[148:151], v[16:31]
	ds_read_b128 v[242:245], v170 offset:32
	v_exp_f32_e32 v110, v110
	v_exp_f32_e32 v111, v111
	v_add_f32_e32 v193, v110, v193
	v_add_f32_e32 v142, v111, v142
	v_cvt_pk_bf16_f32 v148, v104, v105
	v_cvt_pk_bf16_f32 v149, v106, v107
	v_cvt_pk_bf16_f32 v150, v108, v109
	v_cvt_pk_bf16_f32 v151, v110, v111
	s_waitcnt lgkmcnt(5)
	v_mfma_f32_32x32x16_bf16 v[96:111], v[222:225], v[124:127], 0
	ds_read_b128 v[246:249], v170 offset:64
	s_waitcnt lgkmcnt(5)
	v_mfma_f32_32x32x16_bf16 v[80:95], v[226:229], v[124:127], 0
	ds_read_b128 v[250:253], v170 offset:96
	v_add_u32_e32 v168, s17, v212
	v_lshl_add_u32 v140, v210, 1, v168
	s_waitcnt vmcnt(0)
	ds_write_b64 v140, v[128:129] offset:18432
	v_lshl_add_u32 v128, v211, 1, v168
	ds_write_b64 v140, v[132:133] offset:27648
	ds_write2st64_b64 v128, v[130:131], v[134:135] offset0:36 offset1:54
	v_add_u32_e32 v128, s16, v213
	ds_write_b128 v128, v[144:147]
	s_waitcnt lgkmcnt(0)
	s_barrier
	s_cbranch_scc1 .Latt_exit_a
	s_andn2_b32 s16, 0x80, s6
	s_mulk_i32 s16, 0x90
	v_add_u32_e32 v192, s16, v208
	ds_read_b128 v[222:225], v192 offset:18496
	ds_read_b128 v[226:229], v192 offset:23104
	v_mfma_f32_32x32x16_bf16 v[80:95], v[230:233], v[120:123], v[80:95]
	ds_read_b128 v[230:233], v192 offset:27712
	s_add_i32 s16, s93, 3
	s_cmp_lt_u32 s16, s13
	s_cselect_b32 s86, s16, s92
	s_add_u32 s16, s90, s6
	s_addc_u32 s17, s91, s7
	global_load_dwordx4 v[128:131], v184, s[16:17]
	v_mfma_f32_32x32x16_bf16 v[80:95], v[234:237], v[116:119], v[80:95]
	ds_read_b128 v[234:237], v192 offset:32320
	s_add_u32 s16, s0, s6
	s_addc_u32 s17, s1, s7
	global_load_dwordx4 v[132:135], v184, s[16:17]
	v_mfma_f32_32x32x16_bf16 v[80:95], v[238:241], v[112:115], v[80:95]
	ds_read_b128 v[238:241], v192 offset:18528
	s_lshl_b64 s[16:17], s[86:87], 17
	s_add_u32 s16, s84, s16
	s_addc_u32 s17, s85, s17
	global_load_dwordx4 v[144:147], v182, s[16:17]
	v_mfma_f32_32x32x16_bf16 v[96:111], v[242:245], v[120:123], v[96:111]
	ds_read_b128 v[242:245], v192 offset:23136
	v_mfma_f32_32x32x16_bf16 v[96:111], v[246:249], v[116:119], v[96:111]
	v_mfma_f32_32x32x16_bf16 v[96:111], v[250:253], v[112:115], v[96:111]
	s_branch .Latt_mask_a
.LBB0_508:
	s_andn2_b32 s16, 0x80, s6
	s_mulk_i32 s16, 0x90
	v_add_u32_e32 v192, s16, v208
	ds_read_b128 v[222:225], v192 offset:18496
	ds_read_b128 v[226:229], v192 offset:23104
	ds_read_b128 v[230:233], v192 offset:27712
	ds_read_b128 v[234:237], v192 offset:32320
	ds_read_b128 v[238:241], v192 offset:18528
	ds_read_b128 v[242:245], v192 offset:23136
	s_add_i32 s16, s93, 3
	s_cmp_lt_u32 s16, s13
	s_cselect_b32 s86, s16, s92
	s_add_u32 s16, s90, s6
	s_addc_u32 s17, s91, s7
	global_load_dwordx4 v[128:131], v184, s[16:17]
	s_add_u32 s16, s0, s6
	s_addc_u32 s17, s1, s7
	global_load_dwordx4 v[132:135], v184, s[16:17]
	s_lshl_b64 s[16:17], s[86:87], 17
	s_add_u32 s16, s84, s16
	s_addc_u32 s17, s85, s17
	global_load_dwordx4 v[144:147], v182, s[16:17]
.Latt_mask_a:
	s_and_saveexec_b64 vcc, s[4:5]
	s_cbranch_execz .LBB0_510
	s_nop 11
	v_sub_f32_e32 v111, v111, v15
	v_sub_f32_e32 v110, v110, v14
	v_sub_f32_e32 v109, v109, v13
	v_sub_f32_e32 v108, v108, v12
	v_sub_f32_e32 v107, v107, v11
	v_sub_f32_e32 v106, v106, v10
	v_sub_f32_e32 v105, v105, v9
	v_sub_f32_e32 v104, v104, v8
	v_sub_f32_e32 v103, v103, v7
	v_sub_f32_e32 v102, v102, v6
	v_sub_f32_e32 v101, v101, v5
	v_sub_f32_e32 v100, v100, v4
	v_sub_f32_e32 v99, v99, v3
	v_sub_f32_e32 v98, v98, v2
	v_sub_f32_e32 v97, v97, v1
	v_sub_f32_e32 v96, v96, v0
	v_sub_f32_e32 v95, v95, v15
	v_sub_f32_e32 v94, v94, v14
	v_sub_f32_e32 v93, v93, v13
	v_sub_f32_e32 v92, v92, v12
	v_sub_f32_e32 v91, v91, v11
	v_sub_f32_e32 v90, v90, v10
	v_sub_f32_e32 v89, v89, v9
	v_sub_f32_e32 v88, v88, v8
	v_sub_f32_e32 v87, v87, v7
	v_sub_f32_e32 v86, v86, v6
	v_sub_f32_e32 v85, v85, v5
	v_sub_f32_e32 v84, v84, v4
	v_sub_f32_e32 v83, v83, v3
	v_sub_f32_e32 v82, v82, v2
	v_sub_f32_e32 v81, v81, v1
	v_sub_f32_e32 v80, v80, v0

.LBB0_541:
	s_waitcnt lgkmcnt(5)
	v_mfma_f32_32x32x16_bf16 v[32:47], v[222:225], v[152:155], v[32:47]
	ds_read_b128 v[246:249], v192 offset:27744
	v_exp_f32_e32 v80, v80
	v_exp_f32_e32 v81, v81
	s_and_b32 s16, s15, 64
	s_mulk_i32 s16, 0x90
	v_add_f32_e32 v193, v80, v193
	v_add_f32_e32 v142, v81, v142
	v_add_u32_e32 v170, s16, v208
	s_waitcnt lgkmcnt(5)
	v_mfma_f32_32x32x16_bf16 v[64:79], v[226:229], v[152:155], v[64:79]
	ds_read_b128 v[250:253], v192 offset:32352
	v_exp_f32_e32 v82, v82
	v_exp_f32_e32 v83, v83
	s_add_i32 s77, s77, 1
	s_and_b32 s16, s77, 1
	v_add_f32_e32 v193, v82, v193
	v_add_f32_e32 v142, v83, v142
	s_mul_i32 s17, s16, 0x4800
	s_waitcnt lgkmcnt(5)
	v_mfma_f32_32x32x16_bf16 v[48:63], v[230:233], v[152:155], v[48:63]
	ds_read_b128 v[222:225], v192 offset:18432
	v_exp_f32_e32 v84, v84
	v_exp_f32_e32 v85, v85
	s_mulk_i32 s16, 0x2400
	s_add_i32 s15, s15, 64
	s_add_u32 s6, s6, 0x80
	s_addc_u32 s7, s7, 0
	s_cmp_eq_u32 s14, s77
	v_add_f32_e32 v193, v84, v193
	v_add_f32_e32 v142, v85, v142
	s_waitcnt lgkmcnt(5)
	v_mfma_f32_32x32x16_bf16 v[16:31], v[234:237], v[152:155], v[16:31]
	ds_read_b128 v[226:229], v192 offset:23040
	v_exp_f32_e32 v86, v86
	v_exp_f32_e32 v87, v87
	v_add_f32_e32 v193, v86, v193
	v_add_f32_e32 v142, v87, v142
	v_cvt_pk_bf16_f32 v152, v80, v81
	v_cvt_pk_bf16_f32 v153, v82, v83
	v_cvt_pk_bf16_f32 v154, v84, v85
	v_cvt_pk_bf16_f32 v155, v86, v87
	s_waitcnt lgkmcnt(5)
	v_mfma_f32_32x32x16_bf16 v[32:47], v[238:241], v[156:159], v[32:47]
	ds_read_b128 v[230:233], v192 offset:27648
	v_exp_f32_e32 v88, v88
	v_exp_f32_e32 v89, v89
	v_add_f32_e32 v193, v88, v193
	v_add_f32_e32 v142, v89, v142
	s_waitcnt lgkmcnt(5)
	v_mfma_f32_32x32x16_bf16 v[64:79], v[242:245], v[156:159], v[64:79]
	ds_read_b128 v[234:237], v192 offset:32256
	v_exp_f32_e32 v90, v90
	v_exp_f32_e32 v91, v91
	v_add_f32_e32 v193, v90, v193
	v_add_f32_e32 v142, v91, v142
	s_waitcnt lgkmcnt(5)
	v_mfma_f32_32x32x16_bf16 v[48:63], v[246:249], v[156:159], v[48:63]
	ds_read_b128 v[238:241], v192 offset:18464
	v_exp_f32_e32 v92, v92
	v_exp_f32_e32 v93, v93
	v_add_f32_e32 v193, v92, v193
	v_add_f32_e32 v142, v93, v142
	s_waitcnt lgkmcnt(5)
	v_mfma_f32_32x32x16_bf16 v[16:31], v[250:253], v[156:159], v[16:31]
	ds_read_b128 v[242:245], v192 offset:23072
	v_exp_f32_e32 v94, v94
	v_exp_f32_e32 v95, v95
	v_add_f32_e32 v193, v94, v193
	v_add_f32_e32 v142, v95, v142
	v_cvt_pk_bf16_f32 v156, v88, v89
	v_cvt_pk_bf16_f32 v157, v90, v91
	v_cvt_pk_bf16_f32 v158, v92, v93
	v_cvt_pk_bf16_f32 v159, v94, v95
	s_waitcnt lgkmcnt(5)
	v_mfma_f32_32x32x16_bf16 v[32:47], v[222:225], v[160:163], v[32:47]
	ds_read_b128 v[246:249], v192 offset:27680
	v_exp_f32_e32 v96, v96
	v_exp_f32_e32 v97, v97
	v_add_f32_e32 v193, v96, v193
	v_add_f32_e32 v142, v97, v142
	s_waitcnt lgkmcnt(5)
	v_mfma_f32_32x32x16_bf16 v[64:79], v[226:229], v[160:163], v[64:79]
	ds_read_b128 v[250:253], v192 offset:32288
	v_exp_f32_e32 v98, v98
	v_exp_f32_e32 v99, v99
	v_add_f32_e32 v193, v98, v193
	v_add_f32_e32 v142, v99, v142
	s_waitcnt lgkmcnt(5)
	v_mfma_f32_32x32x16_bf16 v[48:63], v[230:233], v[160:163], v[48:63]
	ds_read_b128 v[222:225], v170
	v_exp_f32_e32 v100, v100
	v_exp_f32_e32 v101, v101
	v_add_f32_e32 v193, v100, v193
	v_add_f32_e32 v142, v101, v142
	s_waitcnt lgkmcnt(5)
	v_mfma_f32_32x32x16_bf16 v[16:31], v[234:237], v[160:163], v[16:31]
	ds_read_b128 v[226:229], v170 offset:4608
	v_exp_f32_e32 v102, v102
	v_exp_f32_e32 v103, v103
	v_add_f32_e32 v193, v102, v193
	v_add_f32_e32 v142, v103, v142
	v_cvt_pk_bf16_f32 v160, v96, v97
	v_cvt_pk_bf16_f32 v161, v98, v99
	v_cvt_pk_bf16_f32 v162, v100, v101
	v_cvt_pk_bf16_f32 v163, v102, v103
	s_waitcnt lgkmcnt(5)
	v_mfma_f32_32x32x16_bf16 v[32:47], v[238:241], v[148:151], v[32:47]
	ds_read_b128 v[230:233], v170 offset:4640
	v_exp_f32_e32 v104, v104
	v_exp_f32_e32 v105, v105
	v_add_f32_e32 v193, v104, v193
	v_add_f32_e32 v142, v105, v142
	s_waitcnt lgkmcnt(5)
	v_mfma_f32_32x32x16_bf16 v[64:79], v[242:245], v[148:151], v[64:79]
	ds_read_b128 v[234:237], v170 offset:4672
	v_exp_f32_e32 v106, v106
	v_exp_f32_e32 v107, v107
	v_add_f32_e32 v193, v106, v193
	v_add_f32_e32 v142, v107, v142
	s_waitcnt lgkmcnt(5)
	v_mfma_f32_32x32x16_bf16 v[48:63], v[246:249], v[148:151], v[48:63]
	ds_read_b128 v[238:241], v170 offset:4704
	v_exp_f32_e32 v108, v108
	v_exp_f32_e32 v109, v109
	v_add_f32_e32 v193, v108, v193
	v_add_f32_e32 v142, v109, v142
	s_waitcnt lgkmcnt(5)
	v_mfma_f32_32x32x16_bf16 v[16:31], v[250:253], v[148:151], v[16:31]
	ds_read_b128 v[242:245], v170 offset:32
	v_exp_f32_e32 v110, v110
	v_exp_f32_e32 v111, v111
	v_add_f32_e32 v193, v110, v193
	v_add_f32_e32 v142, v111, v142
	v_cvt_pk_bf16_f32 v148, v104, v105
	v_cvt_pk_bf16_f32 v149, v106, v107
	v_cvt_pk_bf16_f32 v150, v108, v109
	v_cvt_pk_bf16_f32 v151, v110, v111
	s_waitcnt lgkmcnt(5)
	v_mfma_f32_32x32x16_bf16 v[96:111], v[222:225], v[124:127], 0
	ds_read_b128 v[246:249], v170 offset:64
	s_waitcnt lgkmcnt(5)
	v_mfma_f32_32x32x16_bf16 v[80:95], v[226:229], v[124:127], 0
	ds_read_b128 v[250:253], v170 offset:96
	v_add_u32_e32 v168, s17, v212
	v_lshl_add_u32 v140, v210, 1, v168
	s_waitcnt vmcnt(0)
	ds_write_b64 v140, v[128:129] offset:18432
	v_lshl_add_u32 v128, v211, 1, v168
	ds_write_b64 v140, v[132:133] offset:27648
	ds_write2st64_b64 v128, v[130:131], v[134:135] offset0:36 offset1:54
	v_add_u32_e32 v128, s16, v213
	ds_write_b128 v128, v[144:147]
	s_waitcnt lgkmcnt(0)
	s_barrier
	s_cbranch_scc1 .Latt_exit_b
	s_andn2_b32 s16, 0x80, s6
	s_mulk_i32 s16, 0x90
	v_add_u32_e32 v192, s16, v208
	ds_read_b128 v[222:225], v192 offset:18496
	ds_read_b128 v[226:229], v192 offset:23104
	v_mfma_f32_32x32x16_bf16 v[80:95], v[230:233], v[120:123], v[80:95]
	ds_read_b128 v[230:233], v192 offset:27712
	s_add_i32 s16, s77, 3
	s_cmp_lt_u32 s16, s13
	s_cselect_b32 s86, s16, s76
	s_add_u32 s16, s90, s6
	s_addc_u32 s17, s91, s7
	global_load_dwordx4 v[128:131], v184, s[16:17]
	v_mfma_f32_32x32x16_bf16 v[80:95], v[234:237], v[116:119], v[80:95]
	ds_read_b128 v[234:237], v192 offset:32320
	s_add_u32 s16, s0, s6
	s_addc_u32 s17, s1, s7
	global_load_dwordx4 v[132:135], v184, s[16:17]
	v_mfma_f32_32x32x16_bf16 v[80:95], v[238:241], v[112:115], v[80:95]
	ds_read_b128 v[238:241], v192 offset:18528
	s_lshl_b64 s[16:17], s[86:87], 17
	s_add_u32 s16, s96, s16
	s_addc_u32 s17, s97, s17
	global_load_dwordx4 v[144:147], v182, s[16:17]
	v_mfma_f32_32x32x16_bf16 v[96:111], v[242:245], v[120:123], v[96:111]
	ds_read_b128 v[242:245], v192 offset:23136
	v_mfma_f32_32x32x16_bf16 v[96:111], v[246:249], v[116:119], v[96:111]
	v_mfma_f32_32x32x16_bf16 v[96:111], v[250:253], v[112:115], v[96:111]
	s_branch .Latt_mask_b
.LBB0_542:
	s_andn2_b32 s16, 0x80, s6
	s_mulk_i32 s16, 0x90
	v_add_u32_e32 v192, s16, v208
	ds_read_b128 v[222:225], v192 offset:18496
	ds_read_b128 v[226:229], v192 offset:23104
	ds_read_b128 v[230:233], v192 offset:27712
	ds_read_b128 v[234:237], v192 offset:32320
	ds_read_b128 v[238:241], v192 offset:18528
	ds_read_b128 v[242:245], v192 offset:23136
	s_add_i32 s16, s77, 3
	s_cmp_lt_u32 s16, s13
	s_cselect_b32 s86, s16, s76
	s_add_u32 s16, s90, s6
	s_addc_u32 s17, s91, s7
	global_load_dwordx4 v[128:131], v184, s[16:17]
	s_add_u32 s16, s0, s6
	s_addc_u32 s17, s1, s7
	global_load_dwordx4 v[132:135], v184, s[16:17]
	s_lshl_b64 s[16:17], s[86:87], 17
	s_add_u32 s16, s96, s16
	s_addc_u32 s17, s97, s17
	global_load_dwordx4 v[144:147], v182, s[16:17]
